# win loop: running output kept in fixed registers (as sel)
# baseline (speedup 1.0000x reference)
; DI int tidx() { int t = threadIdx.x; asm volatile("" : "+v"(t)); return t; }
; DI void gemm_wide(const bf16_t* __restrict__ W, int ldw, const bf16_t* __restrict__ X, int ldx, int nkt,
;                   f32x16 (&acc)[4][2], bf16_t* lds) {
;   const int tid = tidx(), lane = tid & 63, wv = tid >> 6, wn = wv & 1, wm = wv >> 1;
;   const int lr = lane & 31, lh = lane >> 5;
;   const int lrow = tid >> 3, lkc = (tid & 7) * 8;
;   const bf16_t* wp = W + (size_t)lrow * ldw + lkc;
;   const bf16_t* xp = X + (size_t)lrow * ldx + lkc;
;   const size_t wst = (size_t)64 * ldw, xst = (size_t)64 * ldx;
;   u32x4 rw0, rw1, rw2, rw3, rx0, rx1, rx2, rx3;
;     ...
;   u32x4 sw0, sw1, sw2, sw3, sx0, sx1, sx2, sx3;
;     ...
;   __syncthreads();
;   GW_GLOAD(0)
;   GW_LSTORE(0)
;   GW_GLOAD(1)
;   GW_GLOAD_B(nkt > 2 ? 2 : nkt - 1)
;   __syncthreads();
.LBB0_267:
	s_mul_i32 s0, s9, 0x88000
	s_mul_hi_i32 s1, s9, 0x88000
	s_add_u32 s0, s4, s0
	s_addc_u32 s1, s5, s1
	s_mul_i32 s28, s8, 0x88000
	s_mul_hi_i32 s29, s8, 0x88000
	s_add_u32 s28, s14, s28
	s_addc_u32 s29, s15, s29
	v_and_b32_e32 v128, 63, v195
	v_lshrrev_b32_e32 v129, 6, v195
	v_and_b32_e32 v130, 31, v128
	v_lshrrev_b32_e32 v131, 5, v128
	v_bfe_u32 v132, v130, 1, 3
	v_lshlrev_b32_e32 v133, 7, v130
	v_xor_b32_e32 v134, v131, v132
	v_lshl_add_u32 v135, v134, 4, v133
	v_and_b32_e32 v136, 1, v129
	v_lshlrev_b32_e32 v136, 14, v136
	v_lshrrev_b32_e32 v137, 1, v129
	v_lshlrev_b32_e32 v137, 13, v137
	v_add_u32_e32 v137, 0x10000, v137
	v_readfirstlane_b32 s98, v129
	v_add_u32_e32 v176, v136, v135
	v_xor_b32_e32 v177, 32, v176
	v_xor_b32_e32 v178, 64, v176
	v_xor_b32_e32 v179, 0x60, v176
	v_add_u32_e32 v180, v137, v135
	v_xor_b32_e32 v181, 32, v180
	v_xor_b32_e32 v182, 64, v180
	v_xor_b32_e32 v183, 0x60, v180
	s_lshl_b32 s98, s98, 12
	s_movk_i32 s100, 2176
	v_lshrrev_b32_e32 v138, 3, v128
	v_lshl_add_u32 v138, v129, 5, v138
	v_mul_lo_u32 v139, v138, s100
	v_and_b32_e32 v140, 7, v128
	v_lshrrev_b32_e32 v141, 4, v128
	v_xor_b32_e32 v142, v140, v141
	v_xor_b32_e32 v143, 4, v142
	v_lshl_add_u32 v184, v142, 4, v139
	v_lshl_add_u32 v185, v143, 4, v139
	v_add_u32_e32 v185, 0x4400, v185
	v_add_u32_e32 v186, 0x8800, v184
	v_add_u32_e32 v187, 0x8800, v185
	s_barrier
	s_mov_b32 m0, s98
	s_nop 0
	global_load_lds_dwordx4 v184, s[0:1]
	s_add_u32 m0, s98, 0x400
	s_nop 0
	global_load_lds_dwordx4 v185, s[0:1]
	s_add_u32 m0, s98, 0x800
	s_nop 0
	global_load_lds_dwordx4 v186, s[0:1]
	s_add_u32 m0, s98, 0xc00
	s_nop 0
	global_load_lds_dwordx4 v187, s[0:1]
	s_add_u32 s0, s0, 0x80
	s_addc_u32 s1, s1, 0
	s_add_u32 m0, s98, 0x10000
	s_nop 0
	global_load_lds_dwordx4 v184, s[28:29]
	s_add_u32 m0, s98, 0x10400
	s_nop 0
	global_load_lds_dwordx4 v185, s[28:29]
	s_add_u32 m0, s98, 0x10800
	s_nop 0
	global_load_lds_dwordx4 v186, s[28:29]
	s_add_u32 m0, s98, 0x10c00
	s_nop 0
	global_load_lds_dwordx4 v187, s[28:29]
	s_add_u32 s28, s28, 0x80
	s_addc_u32 s29, s29, 0
	s_add_u32 m0, s98, 0x8000
	s_nop 0
	global_load_lds_dwordx4 v184, s[0:1]
	s_add_u32 m0, s98, 0x8400
	s_nop 0
	global_load_lds_dwordx4 v185, s[0:1]
	s_add_u32 m0, s98, 0x8800
	s_nop 0
	global_load_lds_dwordx4 v186, s[0:1]
	s_add_u32 m0, s98, 0x8c00
	s_nop 0
	global_load_lds_dwordx4 v187, s[0:1]
	s_add_u32 s0, s0, 0x80
	s_addc_u32 s1, s1, 0
	v_mov_b64_e32 v[112:113], 0
	v_mov_b64_e32 v[114:115], 0
	v_mov_b64_e32 v[116:117], 0
	v_mov_b64_e32 v[118:119], 0
	v_mov_b64_e32 v[120:121], 0
	v_mov_b64_e32 v[122:123], 0
	v_mov_b64_e32 v[124:125], 0
	v_mov_b64_e32 v[126:127], 0
	v_mov_b64_e32 v[80:81], 0
	v_mov_b64_e32 v[82:83], 0
	v_mov_b64_e32 v[84:85], 0
	v_mov_b64_e32 v[86:87], 0
	v_mov_b64_e32 v[88:89], 0
	v_mov_b64_e32 v[90:91], 0
	v_mov_b64_e32 v[92:93], 0
	v_mov_b64_e32 v[94:95], 0
	v_mov_b64_e32 v[96:97], 0
	v_mov_b64_e32 v[98:99], 0
	v_mov_b64_e32 v[100:101], 0
	v_mov_b64_e32 v[102:103], 0
	v_mov_b64_e32 v[104:105], 0
	v_mov_b64_e32 v[106:107], 0
	v_mov_b64_e32 v[108:109], 0
	v_mov_b64_e32 v[110:111], 0
	v_mov_b64_e32 v[64:65], 0
	v_mov_b64_e32 v[66:67], 0
	v_mov_b64_e32 v[68:69], 0
	v_mov_b64_e32 v[70:71], 0
	v_mov_b64_e32 v[72:73], 0
	v_mov_b64_e32 v[74:75], 0
	v_mov_b64_e32 v[76:77], 0
	v_mov_b64_e32 v[78:79], 0
	v_mov_b64_e32 v[48:49], 0
	v_mov_b64_e32 v[50:51], 0
	v_mov_b64_e32 v[52:53], 0
	v_mov_b64_e32 v[54:55], 0
	v_mov_b64_e32 v[56:57], 0
	v_mov_b64_e32 v[58:59], 0
	v_mov_b64_e32 v[60:61], 0
	v_mov_b64_e32 v[62:63], 0
	v_mov_b64_e32 v[16:17], 0
	v_mov_b64_e32 v[18:19], 0
	v_mov_b64_e32 v[20:21], 0
	v_mov_b64_e32 v[22:23], 0
	v_mov_b64_e32 v[24:25], 0
	v_mov_b64_e32 v[26:27], 0
	v_mov_b64_e32 v[28:29], 0
	v_mov_b64_e32 v[30:31], 0
	v_mov_b64_e32 v[32:33], 0
	v_mov_b64_e32 v[34:35], 0
	v_mov_b64_e32 v[36:37], 0
	v_mov_b64_e32 v[38:39], 0
	v_mov_b64_e32 v[40:41], 0
	v_mov_b64_e32 v[42:43], 0
	v_mov_b64_e32 v[44:45], 0
	v_mov_b64_e32 v[46:47], 0
	v_mov_b64_e32 v[0:1], 0
	v_mov_b64_e32 v[2:3], 0
	v_mov_b64_e32 v[4:5], 0
	v_mov_b64_e32 v[6:7], 0
	v_mov_b64_e32 v[8:9], 0
	v_mov_b64_e32 v[10:11], 0
	v_mov_b64_e32 v[12:13], 0
	v_mov_b64_e32 v[14:15], 0
	s_waitcnt vmcnt(4)
	s_barrier
	ds_read_b128 v[144:147], v180 offset:0
	ds_read_b128 v[128:131], v176 offset:0
	ds_read_b128 v[148:151], v180 offset:4096
	ds_read_b128 v[132:135], v176 offset:4096
	ds_read_b128 v[136:139], v176 offset:8192
	ds_read_b128 v[140:143], v176 offset:12288
	s_movk_i32 s99, 7

; DI float xor32(float v) { return __shfl_xor(v, 32); }
; DI void task_nsa(const P& p, int layer, int task, bf16_t* sm, int dm) {
;     ...
;     const float lt = l + xor32(l);
;     const float inv = lt > 0.f ? 1.f / lt : 0.f;
;     {
;       const float sc = g1 * inv;
; #pragma unroll
;       for (int dt = 0; dt < 2; ++dt)
; #pragma unroll
;         for (int i = 0; i < 16; ++i) outl[(dt * 16 + i) * 64] += sc * O[dt][i];
;     }
;   }
;   {
;     const bf16_t* kg = (const bf16_t*)(p.ws + O_KW) + (size_t)b * S_ * 128 + g * 64;
;     const bf16_t* vg = (const bf16_t*)(p.ws + O_VWT) + (size_t)((b * 2 + g) * 64) * S_;
; #pragma unroll
;     for (int dt = 0; dt < 2; ++dt)
; #pragma unroll
;       for (int i = 0; i < 16; ++i) O[dt][i] = 0.f;
;     float m = -1e30f, l = 0.f;
;     const int kt_lo = q0 >= 511 ? (q0 - 511) >> 6 : 0, kt_hi = qb;
;     kv_gload(R, kg, 128, vg, S_, kt_lo * 64);
.LBB0_802:
	ds_bpermute_b32 v0, v91, v140
	v_mov_b32_e32 v97, 0
	v_mov_b32_e32 v96, v97
	v_mov_b32_e32 v88, v97
	v_mov_b32_e32 v99, v97
	s_waitcnt lgkmcnt(0)
	v_add_f32_e32 v2, v140, v0
	v_div_scale_f32 v3, s[0:1], v2, v2, 1.0
	v_rcp_f32_e32 v4, v3
	v_div_scale_f32 v5, vcc, 1.0, v2, 1.0
	ds_read2st64_b32 v[0:1], v95 offset0:220 offset1:221
	v_fma_f32 v6, -v3, v4, 1.0
	v_fmac_f32_e32 v4, v6, v4
	v_mul_f32_e32 v6, v5, v4
	v_fma_f32 v7, -v3, v6, v5
	v_fmac_f32_e32 v6, v7, v4
	v_fma_f32 v3, -v3, v6, v5
	v_div_fmas_f32 v3, v3, v4, v6
	v_div_fixup_f32 v3, v3, v2, 1.0
	v_cmp_lt_f32_e32 vcc, 0, v2
	s_add_i32 s0, s25, 0xfffffe01
	s_ashr_i32 s0, s0, 6
	v_cndmask_b32_e32 v2, 0, v3, vcc
	v_mul_f32_e32 v8, v89, v2
	ds_read2st64_b32 v[2:3], v95 offset0:222 offset1:223
	ds_read2st64_b32 v[4:5], v95 offset0:224 offset1:225
	ds_read2st64_b32 v[6:7], v95 offset0:226 offset1:227
	s_waitcnt lgkmcnt(3)
	v_fma_f32 v0, v130, v8, v0
	v_fmac_f32_e32 v1, v131, v8
	ds_write2st64_b32 v95, v0, v1 offset0:220 offset1:221
	s_waitcnt lgkmcnt(3)
	v_fma_f32 v0, v128, v8, v2
	v_fmac_f32_e32 v3, v129, v8
	ds_write2st64_b32 v95, v0, v3 offset0:222 offset1:223
	s_waitcnt lgkmcnt(3)
	v_fma_f32 v0, v126, v8, v4
	v_fmac_f32_e32 v5, v127, v8
	ds_write2st64_b32 v95, v0, v5 offset0:224 offset1:225
	ds_read2st64_b32 v[0:1], v95 offset0:228 offset1:229
	s_waitcnt lgkmcnt(4)
	v_fma_f32 v2, v124, v8, v6
	v_fmac_f32_e32 v7, v125, v8
	ds_write2st64_b32 v95, v2, v7 offset0:226 offset1:227
	ds_read2st64_b32 v[2:3], v95 offset0:230 offset1:231
	ds_read2st64_b32 v[4:5], v95 offset0:232 offset1:233
	ds_read2st64_b32 v[6:7], v95 offset0:234 offset1:235
	s_waitcnt lgkmcnt(4)
	v_fma_f32 v0, v116, v8, v0
	v_fmac_f32_e32 v1, v117, v8
	ds_write2st64_b32 v95, v0, v1 offset0:228 offset1:229
	s_waitcnt lgkmcnt(3)
	v_fma_f32 v0, v112, v8, v2
	v_fmac_f32_e32 v3, v113, v8
	ds_write2st64_b32 v95, v0, v3 offset0:230 offset1:231
	s_waitcnt lgkmcnt(3)
	v_fma_f32 v0, v110, v8, v4
	v_fmac_f32_e32 v5, v111, v8
	ds_write2st64_b32 v95, v0, v5 offset0:232 offset1:233
	ds_read2st64_b32 v[0:1], v95 offset0:236 offset1:237
	s_waitcnt lgkmcnt(4)
	v_fma_f32 v2, v108, v8, v6
	v_fmac_f32_e32 v7, v109, v8
	ds_write2st64_b32 v95, v2, v7 offset0:234 offset1:235
	ds_read2st64_b32 v[2:3], v95 offset0:238 offset1:239
	ds_read2st64_b32 v[4:5], v95 offset0:240 offset1:241
	ds_read2st64_b32 v[6:7], v95 offset0:242 offset1:243
	s_waitcnt lgkmcnt(4)
	v_fma_f32 v0, v122, v8, v0
	v_fmac_f32_e32 v1, v123, v8
	ds_write2st64_b32 v95, v0, v1 offset0:236 offset1:237
	s_waitcnt lgkmcnt(3)
	v_fma_f32 v0, v120, v8, v2
	v_fmac_f32_e32 v3, v121, v8
	ds_write2st64_b32 v95, v0, v3 offset0:238 offset1:239
	s_waitcnt lgkmcnt(3)
	v_fma_f32 v0, v118, v8, v4
	v_fmac_f32_e32 v5, v119, v8
	ds_write2st64_b32 v95, v0, v5 offset0:240 offset1:241
	ds_read2st64_b32 v[0:1], v95 offset0:244 offset1:245
	s_waitcnt lgkmcnt(4)
	v_fma_f32 v2, v114, v8, v6
	v_fmac_f32_e32 v7, v115, v8
	ds_write2st64_b32 v95, v2, v7 offset0:242 offset1:243
	ds_read2st64_b32 v[2:3], v95 offset0:246 offset1:247
	ds_read2st64_b32 v[4:5], v95 offset0:248 offset1:249
	ds_read2st64_b32 v[6:7], v95 offset0:250 offset1:251
	s_waitcnt lgkmcnt(4)
	v_fma_f32 v0, v106, v8, v0
	v_fmac_f32_e32 v1, v107, v8
	ds_write2st64_b32 v95, v0, v1 offset0:244 offset1:245
	s_waitcnt lgkmcnt(3)
	v_fma_f32 v0, v104, v8, v2
	v_fmac_f32_e32 v3, v105, v8
	ds_write2st64_b32 v95, v0, v3 offset0:246 offset1:247
	s_waitcnt lgkmcnt(3)
	v_fma_f32 v0, v102, v8, v4
	v_fmac_f32_e32 v5, v103, v8
	s_cmp_gt_u32 s35, 7
	ds_write2st64_b32 v95, v0, v5 offset0:248 offset1:249
	s_waitcnt lgkmcnt(3)
	v_fma_f32 v0, v100, v8, v6
	v_fmac_f32_e32 v7, v101, v8
	s_cselect_b32 s45, s0, 0
	ds_write2st64_b32 v95, v0, v7 offset0:250 offset1:251
	v_mov_b32_e32 v0, v195
	s_cmp_gt_i32 s45, s35
	v_mov_b32_e32 v89, v97
	v_mov_b32_e32 v98, v97
	v_mov_b32_e32 v101, v97
	v_mov_b32_e32 v100, v97
	v_mov_b32_e32 v103, v97
	v_mov_b32_e32 v102, v97
	v_mov_b32_e32 v105, v97
	v_mov_b32_e32 v104, v97
	v_mov_b32_e32 v109, v97
	v_mov_b32_e32 v108, v97
	v_mov_b32_e32 v113, v97
	v_mov_b32_e32 v112, v97
	v_mov_b32_e32 v107, v97
	v_mov_b32_e32 v106, v97
	v_mov_b32_e32 v111, v97
	v_mov_b32_e32 v110, v97
	v_mov_b32_e32 v115, v97
	v_mov_b32_e32 v114, v97
	v_mov_b32_e32 v117, v97
	v_mov_b32_e32 v116, v97
	v_mov_b32_e32 v119, v97
	v_mov_b32_e32 v118, v97
	v_mov_b32_e32 v121, v97
	v_mov_b32_e32 v120, v97
	v_mov_b32_e32 v123, v97
	v_mov_b32_e32 v122, v97
	v_mov_b32_e32 v125, v97
	v_mov_b32_e32 v124, v97
	v_mov_b32_e32 v131, v97
	s_cbranch_scc1 .LBB0_885
	s_lshl_b32 s0, s44, 1
	v_readlane_b32 s2, v253, 36
	v_readlane_b32 s3, v253, 37
	s_add_u32 s0, s2, s0
	s_addc_u32 s1, s3, 0
	s_lshl_b32 s2, s41, 1
	s_add_u32 s2, s0, s2
	s_addc_u32 s3, s1, 0
	s_lshl_b32 s0, s40, 1
	v_readlane_b32 s4, v253, 34
	v_readlane_b32 s5, v253, 35
	s_add_u32 s4, s4, s0
	v_ashrrev_i32_e32 v2, 3, v0
	s_addc_u32 s5, s5, 0
	v_ashrrev_i32_e32 v3, 31, v2
	s_lshl_b32 s6, s45, 6
	v_lshlrev_b64 v[4:5], 13, v[2:3]
	v_add_u32_e32 v2, s6, v2
	v_lshl_add_u64 v[4:5], s[4:5], 0, v[4:5]
	s_ashr_i32 s7, s6, 31
	v_lshlrev_b32_e32 v0, 4, v0
	v_ashrrev_i32_e32 v3, 31, v2
	v_lshl_add_u64 v[4:5], s[6:7], 1, v[4:5]
	v_and_b32_e32 v192, 0x70, v0
	v_lshlrev_b64 v[2:3], 8, v[2:3]
	v_lshl_add_u64 v[0:1], v[4:5], 0, v[192:193]
	v_lshl_add_u64 v[2:3], s[2:3], 0, v[2:3]
	v_lshl_add_u64 v[2:3], v[2:3], 0, v[192:193]
	global_load_dwordx4 v[84:87], v[0:1], off
	global_load_dwordx4 v[80:83], v[2:3], off
	s_sub_i32 s0, s25, 59
	v_add3_u32 v0, s0, v133, v132
	v_mov_b32_e32 v131, 0
	v_add_u32_e32 v127, 0xfffffdc2, v139
	v_add_u32_e32 v128, 0xfffffe1f, v139
	v_subrev_u32_e32 v129, s6, v0
	v_mov_b32_e32 v126, 0xf149f2ca
	v_mov_b32_e32 v124, 0
	v_mov_b32_e32 v125, v131
	v_mov_b32_e32 v122, 0
	v_mov_b32_e32 v123, v131
	v_mov_b32_e32 v120, 0
	v_mov_b32_e32 v121, v131
	v_mov_b32_e32 v118, 0
	v_mov_b32_e32 v119, v131
	v_mov_b32_e32 v116, 0
	v_mov_b32_e32 v117, v131
	v_mov_b32_e32 v114, 0
	v_mov_b32_e32 v115, v131
	v_mov_b32_e32 v110, 0
	v_mov_b32_e32 v111, v131
	v_mov_b32_e32 v106, 0
	v_mov_b32_e32 v107, v131
	v_mov_b32_e32 v112, 0
	v_mov_b32_e32 v113, v131
	v_mov_b32_e32 v108, 0
	v_mov_b32_e32 v109, v131
	v_mov_b32_e32 v104, 0
	v_mov_b32_e32 v105, v131
	v_mov_b32_e32 v102, 0
	v_mov_b32_e32 v103, v131
	v_mov_b32_e32 v100, 0
	v_mov_b32_e32 v101, v131
	v_mov_b32_e32 v98, 0
	v_mov_b32_e32 v99, v131
	v_mov_b32_e32 v88, 0
	v_mov_b32_e32 v89, v131
	v_mov_b32_e32 v96, 0
	v_mov_b32_e32 v97, v131
	v_mov_b64_e32 v[160:161], 0
	v_mov_b64_e32 v[162:163], 0
	v_mov_b64_e32 v[164:165], 0
	v_mov_b64_e32 v[166:167], 0
	v_mov_b64_e32 v[168:169], 0
	v_mov_b64_e32 v[170:171], 0
	v_mov_b64_e32 v[172:173], 0
	v_mov_b64_e32 v[174:175], 0
	v_mov_b64_e32 v[176:177], 0
	v_mov_b64_e32 v[178:179], 0
	v_mov_b64_e32 v[180:181], 0
	v_mov_b64_e32 v[182:183], 0
	v_mov_b64_e32 v[184:185], 0
	v_mov_b64_e32 v[186:187], 0
	v_mov_b64_e32 v[188:189], 0
	v_mov_b64_e32 v[190:191], 0
	s_branch .LBB0_808
; template <int NDT, int MODE, bool ALLON>
; DI void attn_tile(const bf16_t* Kl, int kst, const bf16_t* Vl, const bf16x8 (&q)[4], f32x16 (&O)[NDT], float& m, float& l,
;                   int kbase, int qp, int win, float cbias, const float* tab, bool lane_on) {
;     ...
;     alpha = ex2(m - mn);
;     m = mn;
;     const float mc = (ALLON || lane_on) ? mn - cbias : 1e30f;
; #pragma unroll
;     for (int st = 0; st < 2; ++st)
; #pragma unroll
;       for (int i = 0; i < 16; ++i) { const float pe = ex2(s[st][i] - mc); psum += pe; s[st][i] = pe; }
;   } else {
;     float tmax = -1e30f;
; #pragma unroll
;     for (int st = 0; st < 2; ++st)
; #pragma unroll
;       for (int i = 0; i < 16; ++i) {
;         const int key = kbase + st * 32 + 8 * (i >> 2) + 4 * lh + (i & 3);
;         float v;
;         if (MODE == 1) {
;           const int dist = qp - key;
;           const bool ok = (ALLON || lane_on) && dist >= 0 && dist < win;
;           const int di = dist < 0 ? 0 : (dist > 128 ? 128 : dist);
;           v = ok ? s[st][i] + tab[di] : -1e30f;
;         } else {
;           v = (16 * key + 31 <= qp) ? s[st][i] : -1e30f;
;         }
;         s[st][i] = v;
;         tmax = fmaxf(tmax, v);
;       }
;     tmax = fmaxf(tmax, xor32(tmax));
;     const float mn = fmaxf(m, tmax);
;     alpha = ex2(m - mn);
;     m = mn;
; #pragma unroll
;     for (int st = 0; st < 2; ++st)
; #pragma unroll
; DI void task_nsa(const P& p, int layer, int task, bf16_t* sm, int dm) {
;     ...
;     for (int kt = kt_lo; kt <= kt_hi; ++kt, ++itc) {
;       bf16_t* Kl = sm + (itc & 1) * 9216; bf16_t* Vl = Kl + 4608;
;       kv_lstore(R, Kl, Vl);
;       if (kt < kt_hi) kv_gload(R, kg, 128, vg, S_, (kt + 1) * 64);
;       __syncthreads();
;       if (kt * 64 <= qmin + 31 && kt * 64 + 63 + 511 >= qmin) {
;         if (kt * 64 + 63 + 128 <= qmin && qmin + 31 - kt * 64 < 512)
;           attn_tile<2, 0, true>(Kl, 72, Vl, q, O, m, l, kt * 64, qp, 0, tab[128], tab, true);
;         else
;           attn_tile<2, 1, true>(Kl, 72, Vl, q, O, m, l, kt * 64, qp, 512, 0.f, tab, true);
;       }
;     }
;     const float lt = l + xor32(l);
;     const float inv = 1.f / lt;
;     {
;       const float sc = g2 * inv;
; #pragma unroll
;       for (int dt = 0; dt < 2; ++dt)
; #pragma unroll
;         for (int i = 0; i < 16; ++i) O[dt][i] = outl[(dt * 16 + i) * 64] + sc * O[dt][i];
;     }
.Lwin_home_exit:
	v_mov_b32_e32 v88, v188
	v_mov_b32_e32 v89, v189
	v_mov_b32_e32 v96, v190
	v_mov_b32_e32 v97, v191
	v_mov_b32_e32 v98, v186
	v_mov_b32_e32 v99, v187
	v_mov_b32_e32 v100, v184
	v_mov_b32_e32 v101, v185
	v_mov_b32_e32 v102, v182
	v_mov_b32_e32 v103, v183
	v_mov_b32_e32 v104, v180
	v_mov_b32_e32 v105, v181
	v_mov_b32_e32 v106, v174
	v_mov_b32_e32 v107, v175
	v_mov_b32_e32 v108, v178
	v_mov_b32_e32 v109, v179
	v_mov_b32_e32 v110, v172
	v_mov_b32_e32 v111, v173
	v_mov_b32_e32 v112, v176
	v_mov_b32_e32 v113, v177
	v_mov_b32_e32 v114, v170
	v_mov_b32_e32 v115, v171
	v_mov_b32_e32 v116, v168
	v_mov_b32_e32 v117, v169
	v_mov_b32_e32 v118, v166
	v_mov_b32_e32 v119, v167
	v_mov_b32_e32 v120, v164
	v_mov_b32_e32 v121, v165
	v_mov_b32_e32 v122, v162
	v_mov_b32_e32 v123, v163
	v_mov_b32_e32 v124, v160
	v_mov_b32_e32 v125, v161
	s_branch .LBB0_885
.LBB0_804:
.LBB0_805:
	v_sub_f32_e32 v88, v130, v134
	v_sub_f32_e32 v48, v48, v88
	v_exp_f32_e32 v48, v48
	v_sub_f32_e32 v49, v49, v88
	v_exp_f32_e32 v49, v49
	v_sub_f32_e32 v50, v50, v88
	v_exp_f32_e32 v50, v50
	v_sub_f32_e32 v51, v51, v88
	v_exp_f32_e32 v51, v51
	v_sub_f32_e32 v52, v52, v88
	v_add_f32_e32 v89, 0, v48
	v_exp_f32_e32 v52, v52
	v_sub_f32_e32 v53, v53, v88
	v_add_f32_e32 v89, v49, v89
	v_exp_f32_e32 v53, v53
	v_sub_f32_e32 v54, v54, v88
	v_add_f32_e32 v89, v50, v89
	v_exp_f32_e32 v54, v54
	v_sub_f32_e32 v55, v55, v88
	v_add_f32_e32 v89, v51, v89
	v_exp_f32_e32 v55, v55
	v_sub_f32_e32 v56, v56, v88
	v_add_f32_e32 v89, v52, v89
	v_exp_f32_e32 v56, v56
	v_sub_f32_e32 v57, v57, v88
	v_add_f32_e32 v89, v53, v89
	v_exp_f32_e32 v57, v57
	v_sub_f32_e32 v58, v58, v88
	v_add_f32_e32 v89, v54, v89
	v_exp_f32_e32 v58, v58
	v_sub_f32_e32 v59, v59, v88
	v_add_f32_e32 v89, v55, v89
	v_exp_f32_e32 v59, v59
	v_sub_f32_e32 v60, v60, v88
	v_add_f32_e32 v89, v56, v89
	v_exp_f32_e32 v60, v60
	v_sub_f32_e32 v61, v61, v88
	v_add_f32_e32 v89, v57, v89
	v_exp_f32_e32 v61, v61
	v_sub_f32_e32 v62, v62, v88
	v_add_f32_e32 v89, v58, v89
	v_exp_f32_e32 v62, v62
	v_sub_f32_e32 v63, v63, v88
	v_add_f32_e32 v89, v59, v89
	v_exp_f32_e32 v63, v63
	v_sub_f32_e32 v32, v32, v88
	v_add_f32_e32 v89, v60, v89
	v_exp_f32_e32 v96, v32
	v_add_f32_e32 v89, v61, v89
	v_add_f32_e32 v89, v62, v89
	v_add_f32_e32 v89, v63, v89
	v_sub_f32_e32 v33, v33, v88
	v_add_f32_e32 v32, v96, v89
	v_exp_f32_e32 v89, v33
	v_sub_f32_e32 v33, v34, v88
	v_exp_f32_e32 v97, v33
	v_sub_f32_e32 v33, v35, v88
	v_exp_f32_e32 v98, v33
	v_sub_f32_e32 v33, v36, v88
	v_exp_f32_e32 v99, v33
	v_sub_f32_e32 v33, v37, v88
	v_add_f32_e32 v32, v89, v32
	v_exp_f32_e32 v37, v33
	v_sub_f32_e32 v33, v38, v88
	v_add_f32_e32 v32, v97, v32
	v_exp_f32_e32 v100, v33
	v_sub_f32_e32 v33, v39, v88
	v_add_f32_e32 v32, v98, v32
	v_exp_f32_e32 v101, v33
	v_sub_f32_e32 v33, v40, v88
	v_add_f32_e32 v32, v99, v32
	v_exp_f32_e32 v102, v33
	v_sub_f32_e32 v33, v41, v88
	v_add_f32_e32 v32, v37, v32
	v_exp_f32_e32 v103, v33
	v_sub_f32_e32 v33, v42, v88
	v_add_f32_e32 v32, v100, v32
	v_exp_f32_e32 v104, v33
	v_sub_f32_e32 v33, v43, v88
	v_add_f32_e32 v32, v101, v32
	v_exp_f32_e32 v105, v33
	v_sub_f32_e32 v33, v44, v88
	v_add_f32_e32 v32, v102, v32
	v_exp_f32_e32 v106, v33
	v_sub_f32_e32 v33, v45, v88
	v_add_f32_e32 v32, v103, v32
	v_exp_f32_e32 v107, v33
	v_sub_f32_e32 v33, v46, v88
	v_add_f32_e32 v32, v104, v32
	v_exp_f32_e32 v46, v33
	v_sub_f32_e32 v33, v47, v88
	v_add_f32_e32 v32, v105, v32
	v_exp_f32_e32 v47, v33
	v_add_f32_e32 v32, v106, v32
	v_add_f32_e32 v32, v107, v32
	v_add_f32_e32 v32, v46, v32
	v_add_f32_e32 v36, v47, v32
	v_cvt_pk_bf16_f32 v32, v48, v49
	v_add3_u32 v48, s25, v133, v132
	v_add_u32_e32 v49, 0x2000, v48
	ds_read2_b64 v[38:41], v49 offset0:128 offset1:130
	ds_read2_b64 v[42:45], v49 offset0:132 offset1:134
	v_cvt_pk_bf16_f32 v33, v50, v51
	v_cvt_pk_bf16_f32 v34, v52, v53
	v_cvt_pk_bf16_f32 v35, v54, v55
	v_add_u32_e32 v48, 0x3000, v48
	v_fmac_f32_e32 v36, v131, v126
	s_waitcnt lgkmcnt(1)
	v_mfma_f32_32x32x16_bf16 v[160:175], v[38:41], v[32:35], v[160:175]
	ds_read2_b64 v[38:41], v48 offset0:192 offset1:194
	v_mov_b32_e32 v131, v36
	s_waitcnt lgkmcnt(0)
	v_mfma_f32_32x32x16_bf16 v[176:191], v[38:41], v[32:35], v[176:191]
	ds_read2_b64 v[38:41], v48 offset0:196 offset1:198
	v_cvt_pk_bf16_f32 v32, v56, v57
	v_cvt_pk_bf16_f32 v33, v58, v59
	v_cvt_pk_bf16_f32 v34, v60, v61
	v_cvt_pk_bf16_f32 v35, v62, v63
	s_waitcnt lgkmcnt(0)
	s_nop 0
	v_mfma_f32_32x32x16_bf16 v[176:191], v[38:41], v[32:35], v[176:191]
	ds_read2_b64 v[38:41], v49 offset0:136 offset1:138
	v_mfma_f32_32x32x16_bf16 v[160:175], v[42:45], v[32:35], v[160:175]
	v_cvt_pk_bf16_f32 v32, v96, v89
	v_cvt_pk_bf16_f32 v33, v97, v98
	v_cvt_pk_bf16_f32 v34, v99, v37
	v_cvt_pk_bf16_f32 v35, v100, v101
	s_waitcnt lgkmcnt(0)
	s_nop 0
	v_mfma_f32_32x32x16_bf16 v[160:175], v[38:41], v[32:35], v[160:175]
	ds_read2_b64 v[38:41], v48 offset0:200 offset1:202
	s_waitcnt lgkmcnt(0)
	v_mfma_f32_32x32x16_bf16 v[176:191], v[38:41], v[32:35], v[176:191]
	ds_read2_b64 v[38:41], v49 offset0:140 offset1:142
	v_cvt_pk_bf16_f32 v32, v102, v103
	v_cvt_pk_bf16_f32 v33, v104, v105
	v_cvt_pk_bf16_f32 v34, v106, v107
	v_cvt_pk_bf16_f32 v35, v46, v47
	s_waitcnt lgkmcnt(0)
	s_nop 0
	v_mfma_f32_32x32x16_bf16 v[160:175], v[38:41], v[32:35], v[160:175]
	ds_read2_b64 v[38:41], v48 offset0:204 offset1:206
	s_waitcnt lgkmcnt(0)
	v_mfma_f32_32x32x16_bf16 v[176:191], v[38:41], v[32:35], v[176:191]
	s_nop 8

; DI float ex2(float x) { return __builtin_amdgcn_exp2f(x); }
; DI float xor32(float v) { return __shfl_xor(v, 32); }
; template <int NDT, int MODE, bool ALLON>
; DI void attn_tile(const bf16_t* Kl, int kst, const bf16_t* Vl, const bf16x8 (&q)[4], f32x16 (&O)[NDT], float& m, float& l,
;                   int kbase, int qp, int win, float cbias, const float* tab, bool lane_on) {
;     ...
;   } else {
;     float tmax = -1e30f;
; #pragma unroll
;     for (int st = 0; st < 2; ++st)
; #pragma unroll
;       for (int i = 0; i < 16; ++i) {
;         const int key = kbase + st * 32 + 8 * (i >> 2) + 4 * lh + (i & 3);
;         float v;
;         if (MODE == 1) {
;           const int dist = qp - key;
;           const bool ok = (ALLON || lane_on) && dist >= 0 && dist < win;
;           const int di = dist < 0 ? 0 : (dist > 128 ? 128 : dist);
;           v = ok ? s[st][i] + tab[di] : -1e30f;
;         } else {
;           v = (16 * key + 31 <= qp) ? s[st][i] : -1e30f;
;         }
;         s[st][i] = v;
;         tmax = fmaxf(tmax, v);
;       }
;     tmax = fmaxf(tmax, xor32(tmax));
;     const float mn = fmaxf(m, tmax);
;     alpha = ex2(m - mn);
;     m = mn;
; #pragma unroll
;     for (int st = 0; st < 2; ++st)
; #pragma unroll
;       for (int i = 0; i < 16; ++i) {
;         const float pe = s[st][i] > -5e29f ? ex2(s[st][i] - mn) : 0.f;
;         psum += pe;
;         s[st][i] = pe;
;       }
;   }
;   l = l * alpha + psum;
.LBB0_876:
	s_or_b64 exec, exec, s[30:31]
	v_max3_f32 v0, v134, s93, v63
	v_max3_f32 v0, v0, v133, v58
	v_max3_f32 v0, v0, v132, v56
	v_max3_f32 v0, v0, v62, v54
	v_max3_f32 v0, v0, v60, v51
	v_max3_f32 v0, v0, v57, v48
	v_max3_f32 v0, v0, v55, v46
	v_max3_f32 v0, v0, v52, v43
	v_max3_f32 v0, v0, v49, v40
	v_max3_f32 v0, v0, v47, v38
	v_max3_f32 v0, v0, v45, v37
	v_max3_f32 v0, v0, v42, v36
	v_max3_f32 v0, v0, v39, v35
	v_max3_f32 v0, v0, v44, v41
	v_max3_f32 v0, v0, v53, v50
	v_max3_f32 v0, v0, v61, v59
	ds_bpermute_b32 v1, v91, v0
	s_waitcnt lgkmcnt(0)
	v_max3_f32 v130, v126, v0, v1
	v_sub_f32_e32 v0, v126, v130
	v_exp_f32_e32 v32, v0
	s_nop 0
	v_cmp_neq_f32_e32 vcc, 1.0, v32
	s_cbranch_vccz .LBB0_883
	v_pk_mul_f32 v[160:161], v[160:161], v[32:33] op_sel_hi:[1,0]
	v_pk_mul_f32 v[162:163], v[162:163], v[32:33] op_sel_hi:[1,0]
	v_pk_mul_f32 v[164:165], v[164:165], v[32:33] op_sel_hi:[1,0]
	v_pk_mul_f32 v[166:167], v[166:167], v[32:33] op_sel_hi:[1,0]
	v_pk_mul_f32 v[168:169], v[168:169], v[32:33] op_sel_hi:[1,0]
	v_pk_mul_f32 v[170:171], v[170:171], v[32:33] op_sel_hi:[1,0]
	v_pk_mul_f32 v[172:173], v[172:173], v[32:33] op_sel_hi:[1,0]
	v_pk_mul_f32 v[174:175], v[174:175], v[32:33] op_sel_hi:[1,0]
	v_pk_mul_f32 v[176:177], v[176:177], v[32:33] op_sel_hi:[1,0]
	v_pk_mul_f32 v[178:179], v[178:179], v[32:33] op_sel_hi:[1,0]
	v_pk_mul_f32 v[180:181], v[180:181], v[32:33] op_sel_hi:[1,0]
	v_pk_mul_f32 v[182:183], v[182:183], v[32:33] op_sel_hi:[1,0]
	v_pk_mul_f32 v[184:185], v[184:185], v[32:33] op_sel_hi:[1,0]
	v_pk_mul_f32 v[186:187], v[186:187], v[32:33] op_sel_hi:[1,0]
	v_pk_mul_f32 v[188:189], v[188:189], v[32:33] op_sel_hi:[1,0]
	v_pk_mul_f32 v[190:191], v[190:191], v[32:33] op_sel_hi:[1,0]
	s_cbranch_execnz .LBB0_879
.LBB0_878:
.LBB0_879:
	v_sub_f32_e32 v88, v134, v130
	v_exp_f32_e32 v88, v88
	v_cmp_lt_f32_e32 vcc, s11, v134
	s_nop 1
	v_cndmask_b32_e32 v88, 0, v88, vcc
	v_cmp_lt_f32_e32 vcc, s11, v63
	v_sub_f32_e32 v63, v63, v130
	v_exp_f32_e32 v63, v63
	v_add_f32_e32 v89, 0, v88
	v_cndmask_b32_e32 v63, 0, v63, vcc
	v_add_f32_e32 v96, v63, v89
	v_sub_f32_e32 v89, v133, v130
	v_exp_f32_e32 v89, v89
	v_cmp_lt_f32_e32 vcc, s11, v133
	s_nop 1
	v_cndmask_b32_e32 v89, 0, v89, vcc
	v_cmp_lt_f32_e32 vcc, s11, v58
	v_sub_f32_e32 v58, v58, v130
	v_exp_f32_e32 v58, v58
	v_add_f32_e32 v96, v89, v96
	v_cndmask_b32_e32 v58, 0, v58, vcc
	v_add_f32_e32 v97, v58, v96
	v_sub_f32_e32 v96, v132, v130
	v_exp_f32_e32 v96, v96
	v_cmp_lt_f32_e32 vcc, s11, v132
	s_nop 1
	v_cndmask_b32_e32 v96, 0, v96, vcc
	v_cmp_lt_f32_e32 vcc, s11, v56
	v_sub_f32_e32 v56, v56, v130
	v_exp_f32_e32 v56, v56
	v_add_f32_e32 v98, v96, v97
	v_cndmask_b32_e32 v97, 0, v56, vcc
	v_cmp_lt_f32_e32 vcc, s11, v62
	v_sub_f32_e32 v62, v62, v130
	v_exp_f32_e32 v62, v62
	v_add_f32_e32 v56, v97, v98
	v_cndmask_b32_e32 v62, 0, v62, vcc
	v_cmp_lt_f32_e32 vcc, s11, v54
	v_sub_f32_e32 v54, v54, v130
	v_exp_f32_e32 v54, v54
	v_add_f32_e32 v56, v62, v56
	v_cndmask_b32_e32 v98, 0, v54, vcc
	v_sub_f32_e32 v54, v60, v130
	v_exp_f32_e32 v54, v54
	v_cmp_lt_f32_e32 vcc, s11, v60
	v_add_f32_e32 v56, v98, v56
	s_nop 0
	v_cndmask_b32_e32 v54, 0, v54, vcc
	v_cmp_lt_f32_e32 vcc, s11, v51
	v_sub_f32_e32 v51, v51, v130
	v_exp_f32_e32 v51, v51
	v_add_f32_e32 v56, v54, v56
	v_cndmask_b32_e32 v51, 0, v51, vcc
	v_add_f32_e32 v60, v51, v56
	v_sub_f32_e32 v56, v57, v130
	v_exp_f32_e32 v56, v56
	v_cmp_lt_f32_e32 vcc, s11, v57
	s_nop 1
	v_cndmask_b32_e32 v56, 0, v56, vcc
	v_cmp_lt_f32_e32 vcc, s11, v48
	v_sub_f32_e32 v48, v48, v130
	v_exp_f32_e32 v48, v48
	v_add_f32_e32 v57, v56, v60
	v_cndmask_b32_e32 v48, 0, v48, vcc
	v_cmp_lt_f32_e32 vcc, s11, v55
	v_sub_f32_e32 v55, v55, v130
	v_exp_f32_e32 v55, v55
	v_add_f32_e32 v57, v48, v57
	v_cndmask_b32_e32 v55, 0, v55, vcc
	v_cmp_lt_f32_e32 vcc, s11, v46
	v_sub_f32_e32 v46, v46, v130
	v_exp_f32_e32 v46, v46
	v_add_f32_e32 v57, v55, v57
	v_cndmask_b32_e32 v46, 0, v46, vcc
	v_cmp_lt_f32_e32 vcc, s11, v52
	v_sub_f32_e32 v52, v52, v130
	v_exp_f32_e32 v52, v52
	v_add_f32_e32 v57, v46, v57
	v_cndmask_b32_e32 v52, 0, v52, vcc
	v_cmp_lt_f32_e32 vcc, s11, v43
	v_sub_f32_e32 v43, v43, v130
	v_exp_f32_e32 v43, v43
	v_add_f32_e32 v57, v52, v57
	v_cndmask_b32_e32 v43, 0, v43, vcc
	v_cmp_lt_f32_e32 vcc, s11, v49
	v_sub_f32_e32 v49, v49, v130
	v_exp_f32_e32 v49, v49
	v_add_f32_e32 v57, v43, v57
	v_cndmask_b32_e32 v49, 0, v49, vcc
	v_cmp_lt_f32_e32 vcc, s11, v40
	v_sub_f32_e32 v40, v40, v130
	v_exp_f32_e32 v40, v40
	v_add_f32_e32 v57, v49, v57
	v_cndmask_b32_e32 v40, 0, v40, vcc
	v_cmp_lt_f32_e32 vcc, s11, v47
	v_sub_f32_e32 v47, v47, v130
	v_exp_f32_e32 v47, v47
	v_add_f32_e32 v57, v40, v57
	v_cndmask_b32_e32 v47, 0, v47, vcc
	v_cmp_lt_f32_e32 vcc, s11, v38
	v_sub_f32_e32 v38, v38, v130
	v_exp_f32_e32 v38, v38
	v_add_f32_e32 v57, v47, v57
	v_cndmask_b32_e32 v100, 0, v38, vcc
	v_cmp_lt_f32_e32 vcc, s11, v45
	v_sub_f32_e32 v45, v45, v130
	v_exp_f32_e32 v45, v45
	v_add_f32_e32 v38, v100, v57
	v_cndmask_b32_e32 v57, 0, v45, vcc
	v_cmp_lt_f32_e32 vcc, s11, v37
	v_sub_f32_e32 v37, v37, v130
	v_exp_f32_e32 v37, v37
	v_add_f32_e32 v38, v57, v38
	v_cndmask_b32_e32 v101, 0, v37, vcc
	v_add_f32_e32 v37, v101, v38
	v_sub_f32_e32 v38, v42, v130
	v_exp_f32_e32 v38, v38
	v_cmp_lt_f32_e32 vcc, s11, v42
	s_nop 1
	v_cndmask_b32_e32 v102, 0, v38, vcc
	v_cmp_lt_f32_e32 vcc, s11, v36
	v_sub_f32_e32 v36, v36, v130
	v_exp_f32_e32 v36, v36
	v_add_f32_e32 v37, v102, v37
	v_cvt_pk_bf16_f32 v38, v96, v97
	v_cndmask_b32_e32 v103, 0, v36, vcc
	v_add_f32_e32 v36, v103, v37
	v_sub_f32_e32 v37, v39, v130
	v_exp_f32_e32 v37, v37
	v_cmp_lt_f32_e32 vcc, s11, v39
	v_cvt_pk_bf16_f32 v39, v62, v98
	s_nop 0
; DI float ex2(float x) { return __builtin_amdgcn_exp2f(x); }
; template <int NDT, int MODE, bool ALLON>
; DI void attn_tile(const bf16_t* Kl, int kst, const bf16_t* Vl, const bf16x8 (&q)[4], f32x16 (&O)[NDT], float& m, float& l,
;                   int kbase, int qp, int win, float cbias, const float* tab, bool lane_on) {
;     ...
;   for (int ks = 0; ks < 4; ++ks) {
;     const bf16x8 k0 = *(const bf16x8*)(Kl + lr * kst + ks * 16 + lh * 8);
;     const bf16x8 k1 = *(const bf16x8*)(Kl + (32 + lr) * kst + ks * 16 + lh * 8);
;     s[0] = MFMA32(k0, q[ks], s[0]);
;     s[1] = MFMA32(k1, q[ks], s[1]);
;   }
;   float alpha, psum = 0.f;
;   if (MODE == 0) {
;     float tmax = fmaxf(s[0][0], s[1][0]);
; #pragma unroll
;     for (int i = 1; i < 16; ++i) tmax = fmaxf(tmax, fmaxf(s[0][i], s[1][i]));
;     tmax = fmaxf(tmax, xor32(tmax)) + cbias;
;     if (!ALLON) tmax = lane_on ? tmax : -1e30f;
;     const float mn = fmaxf(m, tmax);
;     alpha = ex2(m - mn);
;     m = mn;
;     const float mc = (ALLON || lane_on) ? mn - cbias : 1e30f;
; #pragma unroll
;     for (int st = 0; st < 2; ++st)
; #pragma unroll
;     ...
; #pragma unroll
;     for (int st = 0; st < 2; ++st)
; #pragma unroll
;       for (int i = 0; i < 16; ++i) {
;         const float pe = s[st][i] > -5e29f ? ex2(s[st][i] - mn) : 0.f;
;         psum += pe;
;         s[st][i] = pe;
;       }
;   }
;   l = l * alpha + psum;
;   if (__ballot(alpha != 1.f)) {
; #pragma unroll
;     for (int dt = 0; dt < NDT; ++dt)
; #pragma unroll
;       for (int i = 0; i < 16; ++i) O[dt][i] *= alpha;
;   }
; #pragma unroll
;   for (int st = 0; st < 2; ++st)
; #pragma unroll
;     for (int sk = 0; sk < 2; ++sk) {
;       u32x4 pu;
;       pu[0] = pack2(s[st][8 * sk + 0], s[st][8 * sk + 1]);
;       pu[1] = pack2(s[st][8 * sk + 2], s[st][8 * sk + 3]);
;       pu[2] = pack2(s[st][8 * sk + 4], s[st][8 * sk + 5]);
;       pu[3] = pack2(s[st][8 * sk + 6], s[st][8 * sk + 7]);
;       const bf16x8 pf = __builtin_bit_cast(bf16x8, pu);
; #pragma unroll
;       for (int dt = 0; dt < NDT; ++dt) {
;         const bf16_t* vp = Vl + (dt * 32 + lr) * 72 + st * 32 + sk * 16 + 4 * lh;
;         const uint2 v0 = *(const uint2*)(vp);
;         const uint2 v1 = *(const uint2*)(vp + 8);
;         u32x4 vu; vu[0] = v0.x; vu[1] = v0.y; vu[2] = v1.x; vu[3] = v1.y;
;         O[dt] = MFMA32(__builtin_bit_cast(bf16x8, vu), pf, O[dt]);
;       }
	v_cndmask_b32_e32 v104, 0, v37, vcc
	v_cmp_lt_f32_e32 vcc, s11, v35
	v_sub_f32_e32 v35, v35, v130
	v_exp_f32_e32 v35, v35
	v_add_f32_e32 v36, v104, v36
	v_cvt_pk_bf16_f32 v37, v89, v58
	v_cndmask_b32_e32 v105, 0, v35, vcc
	v_add_f32_e32 v35, v105, v36
	v_sub_f32_e32 v36, v44, v130
	v_exp_f32_e32 v36, v36
	v_cmp_lt_f32_e32 vcc, s11, v44
	s_nop 1
	v_cndmask_b32_e32 v106, 0, v36, vcc
	v_sub_f32_e32 v36, v41, v130
	v_exp_f32_e32 v36, v36
	v_cmp_lt_f32_e32 vcc, s11, v41
	v_add_f32_e32 v35, v106, v35
	s_nop 0
	v_cndmask_b32_e32 v107, 0, v36, vcc
	v_sub_f32_e32 v36, v53, v130
	v_exp_f32_e32 v36, v36
	v_cmp_lt_f32_e32 vcc, s11, v53
	v_add_f32_e32 v35, v107, v35
	s_nop 0
	v_cndmask_b32_e32 v53, 0, v36, vcc
	v_sub_f32_e32 v36, v50, v130
	v_exp_f32_e32 v36, v36
	v_cmp_lt_f32_e32 vcc, s11, v50
	v_add_f32_e32 v35, v53, v35
	s_nop 0
	v_cndmask_b32_e32 v50, 0, v36, vcc
	v_sub_f32_e32 v36, v61, v130
	v_exp_f32_e32 v36, v36
	v_cmp_lt_f32_e32 vcc, s11, v61
	v_add_f32_e32 v35, v50, v35
	s_nop 0
	v_cndmask_b32_e32 v108, 0, v36, vcc
	v_sub_f32_e32 v36, v59, v130
	v_exp_f32_e32 v36, v36
	v_cmp_lt_f32_e32 vcc, s11, v59
	v_add_f32_e32 v35, v108, v35
	s_nop 0
	v_cndmask_b32_e32 v109, 0, v36, vcc
	v_add_f32_e32 v35, v109, v35
	v_fmac_f32_e32 v35, v131, v32
	v_lshlrev_b32_e32 v32, 3, v34
	v_add3_u32 v32, s25, v32, v33
	v_add_u32_e32 v33, 0x2000, v32
	ds_read2_b64 v[58:61], v33 offset0:128 offset1:130
	ds_read2_b64 v[96:99], v33 offset0:132 offset1:134
	v_cvt_pk_bf16_f32 v36, v88, v63
	v_add_u32_e32 v32, 0x3000, v32
	v_mov_b32_e32 v131, v35
	s_waitcnt lgkmcnt(1)
	v_mfma_f32_32x32x16_bf16 v[160:175], v[58:61], v[36:39], v[160:175]
	ds_read2_b64 v[58:61], v32 offset0:192 offset1:194
	s_waitcnt lgkmcnt(0)
	v_mfma_f32_32x32x16_bf16 v[176:191], v[58:61], v[36:39], v[176:191]
	v_cvt_pk_bf16_f32 v39, v52, v43
	ds_read2_b64 v[42:45], v32 offset0:196 offset1:198
	v_cvt_pk_bf16_f32 v36, v54, v51
	v_cvt_pk_bf16_f32 v37, v56, v48
	v_cvt_pk_bf16_f32 v38, v55, v46
	s_nop 1
	v_mfma_f32_32x32x16_bf16 v[160:175], v[96:99], v[36:39], v[160:175]
	s_waitcnt lgkmcnt(0)
	v_mfma_f32_32x32x16_bf16 v[176:191], v[42:45], v[36:39], v[176:191]
	v_cvt_pk_bf16_f32 v36, v49, v40
	ds_read2_b64 v[40:43], v33 offset0:136 offset1:138
	v_cvt_pk_bf16_f32 v37, v47, v100
	v_cvt_pk_bf16_f32 v38, v57, v101
	v_cvt_pk_bf16_f32 v39, v102, v103
	s_waitcnt lgkmcnt(0)
	s_nop 0
	v_mfma_f32_32x32x16_bf16 v[160:175], v[40:43], v[36:39], v[160:175]
	ds_read2_b64 v[40:43], v32 offset0:200 offset1:202
	s_waitcnt lgkmcnt(0)
	v_mfma_f32_32x32x16_bf16 v[176:191], v[40:43], v[36:39], v[176:191]
	ds_read2_b64 v[40:43], v33 offset0:140 offset1:142
	v_cvt_pk_bf16_f32 v36, v104, v105
	v_cvt_pk_bf16_f32 v37, v106, v107
	v_cvt_pk_bf16_f32 v38, v53, v50
	v_cvt_pk_bf16_f32 v39, v108, v109
	s_waitcnt lgkmcnt(0)
	s_nop 0
	v_mfma_f32_32x32x16_bf16 v[160:175], v[40:43], v[36:39], v[160:175]
	ds_read2_b64 v[40:43], v32 offset0:204 offset1:206
	s_waitcnt lgkmcnt(0)
	v_mfma_f32_32x32x16_bf16 v[176:191], v[40:43], v[36:39], v[176:191]
	s_nop 8
.LBB0_880:
	s_andn2_saveexec_b64 s[0:1], s[0:1]
	s_cbranch_execz .LBB0_806
	v_mov_b32_e32 v0, v195
	ds_read_b32 v134, v135 offset:37376
	s_nop 0
	v_and_b32_e32 v1, 31, v0
	v_lshrrev_b32_e32 v0, 2, v0
	v_mul_u32_u24_e32 v1, 0x48, v1
	v_and_b32_e32 v133, 8, v0
	v_lshlrev_b32_e32 v132, 1, v1
	v_lshlrev_b32_e32 v0, 1, v133
	v_add3_u32 v4, s25, v132, v0
	ds_read_b128 v[0:3], v4
	s_waitcnt lgkmcnt(0)
	v_mfma_f32_32x32x16_bf16 v[48:63], v[0:3], v[64:67], 0
	ds_read_b128 v[0:3], v4 offset:4608
	s_waitcnt lgkmcnt(0)
	v_mfma_f32_32x32x16_bf16 v[32:47], v[0:3], v[64:67], 0
	ds_read_b128 v[0:3], v4 offset:32
	s_waitcnt lgkmcnt(0)
	v_mfma_f32_32x32x16_bf16 v[48:63], v[0:3], v[68:71], v[48:63]
	ds_read_b128 v[0:3], v4 offset:4640
	s_waitcnt lgkmcnt(0)
	v_mfma_f32_32x32x16_bf16 v[32:47], v[0:3], v[68:71], v[32:47]
	ds_read_b128 v[0:3], v4 offset:64
	s_waitcnt lgkmcnt(0)
	v_mfma_f32_32x32x16_bf16 v[48:63], v[0:3], v[72:75], v[48:63]
	ds_read_b128 v[0:3], v4 offset:4672
	s_waitcnt lgkmcnt(0)
	v_mfma_f32_32x32x16_bf16 v[32:47], v[0:3], v[72:75], v[32:47]
	ds_read_b128 v[0:3], v4 offset:4704
	s_waitcnt lgkmcnt(0)
	v_mfma_f32_32x32x16_bf16 v[32:47], v[0:3], v[76:79], v[32:47]
	ds_read_b128 v[0:3], v4 offset:96
	s_waitcnt lgkmcnt(0)
	v_mfma_f32_32x32x16_bf16 v[48:63], v[0:3], v[76:79], v[48:63]
	s_nop 8
	v_max3_f32 v0, v32, v33, v34
	v_max3_f32 v0, v0, v35, v36
	v_max3_f32 v0, v0, v37, v38
	v_max3_f32 v0, v0, v39, v40
	v_max3_f32 v0, v0, v41, v42
	v_max3_f32 v0, v0, v43, v44
	v_max3_f32 v0, v0, v45, v46
	v_max_f32_e32 v0, v0, v47
	v_max3_f32 v1, v48, v49, v50
	v_max3_f32 v1, v1, v51, v52
	v_max3_f32 v1, v1, v53, v54
	v_max3_f32 v1, v1, v55, v56
	v_max3_f32 v1, v1, v57, v58
	v_max3_f32 v1, v1, v59, v60
	v_max3_f32 v1, v1, v61, v62
	v_max_f32_e32 v1, v1, v63
	v_max_f32_e32 v0, v0, v1
	ds_bpermute_b32 v1, v91, v0
	s_waitcnt lgkmcnt(0)
	v_max_f32_e32 v1, v1, v1
	v_max_f32_e32 v0, v0, v1
	v_add_f32_e32 v0, v134, v0
	v_max_f32_e32 v1, v126, v126
	v_max_f32_e32 v130, v1, v0
	v_sub_f32_e32 v0, v126, v130
	v_exp_f32_e32 v126, v0
	s_nop 0
	v_cmp_neq_f32_e32 vcc, 1.0, v126
	s_cbranch_vccz .LBB0_884
	v_pk_mul_f32 v[160:161], v[160:161], v[126:127] op_sel_hi:[1,0]
	v_pk_mul_f32 v[162:163], v[162:163], v[126:127] op_sel_hi:[1,0]
	v_pk_mul_f32 v[164:165], v[164:165], v[126:127] op_sel_hi:[1,0]
	v_pk_mul_f32 v[166:167], v[166:167], v[126:127] op_sel_hi:[1,0]
	v_pk_mul_f32 v[168:169], v[168:169], v[126:127] op_sel_hi:[1,0]
	v_pk_mul_f32 v[170:171], v[170:171], v[126:127] op_sel_hi:[1,0]
	v_pk_mul_f32 v[172:173], v[172:173], v[126:127] op_sel_hi:[1,0]
	v_pk_mul_f32 v[174:175], v[174:175], v[126:127] op_sel_hi:[1,0]
	v_pk_mul_f32 v[176:177], v[176:177], v[126:127] op_sel_hi:[1,0]
	v_pk_mul_f32 v[178:179], v[178:179], v[126:127] op_sel_hi:[1,0]
	v_pk_mul_f32 v[180:181], v[180:181], v[126:127] op_sel_hi:[1,0]
	v_pk_mul_f32 v[182:183], v[182:183], v[126:127] op_sel_hi:[1,0]
	v_pk_mul_f32 v[184:185], v[184:185], v[126:127] op_sel_hi:[1,0]
	v_pk_mul_f32 v[186:187], v[186:187], v[126:127] op_sel_hi:[1,0]
	v_pk_mul_f32 v[188:189], v[188:189], v[126:127] op_sel_hi:[1,0]
	v_pk_mul_f32 v[190:191], v[190:191], v[126:127] op_sel_hi:[1,0]
	s_cbranch_execnz .LBB0_805
	s_branch .LBB0_804

; DI int tidx() { int t = threadIdx.x; asm volatile("" : "+v"(t)); return t; }
; DI void gemm_wide(const bf16_t* __restrict__ W, int ldw, const bf16_t* __restrict__ X, int ldx, int nkt,
;                   f32x16 (&acc)[4][2], bf16_t* lds) {
;   const int tid = tidx(), lane = tid & 63, wv = tid >> 6, wn = wv & 1, wm = wv >> 1;
;   const int lr = lane & 31, lh = lane >> 5;
;   const int lrow = tid >> 3, lkc = (tid & 7) * 8;
;   const bf16_t* wp = W + (size_t)lrow * ldw + lkc;
;   const bf16_t* xp = X + (size_t)lrow * ldx + lkc;
;   const size_t wst = (size_t)64 * ldw, xst = (size_t)64 * ldx;
;   u32x4 rw0, rw1, rw2, rw3, rx0, rx1, rx2, rx3;
;     ...
;   u32x4 sw0, sw1, sw2, sw3, sx0, sx1, sx2, sx3;
;     ...
;   __syncthreads();
;   GW_GLOAD(0)
;   GW_LSTORE(0)
;   GW_GLOAD(1)
;   GW_GLOAD_B(nkt > 2 ? 2 : nkt - 1)
;   __syncthreads();
; DI void phase_resid(const P& p, const bf16_t* W, const bf16_t* X, int K, bf16_t* sm, const Geo& ge, bool last) {
;     ...
;   TileWalk tw(4, ge);
;   int mt_, nt_;
;   while (tw.next(mt_, nt_)) {
;     f32x16 acc[4][2]; zero_acc8(acc);
;     const int ldk = K + 64;
;     gemm_wide(W + (size_t)nt_ * 256 * ldk, ldk, X + (size_t)mt_ * 256 * ldk, ldk, K / 64, acc, sm);
.LBB0_1104:
	s_cmp_gt_i32 s8, 63
	s_cselect_b64 s[0:1], -1, 0
	s_cmp_lt_i32 s8, 64
	s_mov_b64 s[4:5], -1
	s_mov_b32 s9, s54
	s_cbranch_scc0 .LBB0_1126
	s_ashr_i32 s9, s8, 3
	s_cmp_lt_i32 s9, 4
	s_cbranch_scc0 .LBB0_1125
	s_and_b32 s5, s8, 7
	s_or_b32 s4, s5, s55
	s_mul_i32 s26, s9, 0x88000
	s_mul_hi_i32 s25, s9, 0x88000
	s_add_u32 s26, s6, s26
	s_addc_u32 s27, s7, s25
	s_mul_i32 s25, s4, 0x88000
	s_add_u32 s28, s56, s25
	s_addc_u32 s29, s57, 0
	v_and_b32_e32 v128, 63, v195
	v_lshrrev_b32_e32 v129, 6, v195
	v_and_b32_e32 v130, 31, v128
	v_lshrrev_b32_e32 v131, 5, v128
	v_bfe_u32 v132, v130, 1, 3
	v_lshlrev_b32_e32 v133, 7, v130
	v_xor_b32_e32 v134, v131, v132
	v_lshl_add_u32 v135, v134, 4, v133
	v_and_b32_e32 v136, 1, v129
	v_lshlrev_b32_e32 v136, 14, v136
	v_lshrrev_b32_e32 v137, 1, v129
	v_lshlrev_b32_e32 v137, 13, v137
	v_add_u32_e32 v137, 0x10000, v137
	v_readfirstlane_b32 s98, v129
	v_add_u32_e32 v176, v136, v135
	v_xor_b32_e32 v177, 32, v176
	v_xor_b32_e32 v178, 64, v176
	v_xor_b32_e32 v179, 0x60, v176
	v_add_u32_e32 v180, v137, v135
	v_xor_b32_e32 v181, 32, v180
	v_xor_b32_e32 v182, 64, v180
	v_xor_b32_e32 v183, 0x60, v180
	s_lshl_b32 s98, s98, 12
	s_movk_i32 s100, 2176
	v_lshrrev_b32_e32 v138, 3, v128
	v_lshl_add_u32 v138, v129, 5, v138
	v_mul_lo_u32 v139, v138, s100
	v_and_b32_e32 v140, 7, v128
	v_lshrrev_b32_e32 v141, 4, v128
	v_xor_b32_e32 v142, v140, v141
	v_xor_b32_e32 v143, 4, v142
	v_lshl_add_u32 v184, v142, 4, v139
	v_lshl_add_u32 v185, v143, 4, v139
	v_add_u32_e32 v185, 0x4400, v185
	v_add_u32_e32 v186, 0x8800, v184
	v_add_u32_e32 v187, 0x8800, v185
	s_barrier
	s_mov_b32 m0, s98
	s_nop 0
	global_load_lds_dwordx4 v184, s[26:27]
	s_add_u32 m0, s98, 0x400
	s_nop 0
	global_load_lds_dwordx4 v185, s[26:27]
	s_add_u32 m0, s98, 0x800
	s_nop 0
	global_load_lds_dwordx4 v186, s[26:27]
	s_add_u32 m0, s98, 0xc00
	s_nop 0
	global_load_lds_dwordx4 v187, s[26:27]
	s_add_u32 s26, s26, 0x80
	s_addc_u32 s27, s27, 0
	s_add_u32 m0, s98, 0x10000
	s_nop 0
	global_load_lds_dwordx4 v184, s[28:29]
	s_add_u32 m0, s98, 0x10400
	s_nop 0
	global_load_lds_dwordx4 v185, s[28:29]
	s_add_u32 m0, s98, 0x10800
	s_nop 0
	global_load_lds_dwordx4 v186, s[28:29]
	s_add_u32 m0, s98, 0x10c00
	s_nop 0
	global_load_lds_dwordx4 v187, s[28:29]
	s_add_u32 s28, s28, 0x80
	s_addc_u32 s29, s29, 0
	s_add_u32 m0, s98, 0x8000
	s_nop 0
	global_load_lds_dwordx4 v184, s[26:27]
	s_add_u32 m0, s98, 0x8400
	s_nop 0
	global_load_lds_dwordx4 v185, s[26:27]
	s_add_u32 m0, s98, 0x8800
	s_nop 0
	global_load_lds_dwordx4 v186, s[26:27]
	s_add_u32 m0, s98, 0x8c00
	s_nop 0
	global_load_lds_dwordx4 v187, s[26:27]
	s_add_u32 s26, s26, 0x80
	s_addc_u32 s27, s27, 0
	v_mov_b64_e32 v[112:113], 0
	v_mov_b64_e32 v[114:115], 0
	v_mov_b64_e32 v[116:117], 0
	v_mov_b64_e32 v[118:119], 0
	v_mov_b64_e32 v[120:121], 0
	v_mov_b64_e32 v[122:123], 0
	v_mov_b64_e32 v[124:125], 0
	v_mov_b64_e32 v[126:127], 0
	v_mov_b64_e32 v[80:81], 0
	v_mov_b64_e32 v[82:83], 0
	v_mov_b64_e32 v[84:85], 0
	v_mov_b64_e32 v[86:87], 0
	v_mov_b64_e32 v[88:89], 0
	v_mov_b64_e32 v[90:91], 0
	v_mov_b64_e32 v[92:93], 0
	v_mov_b64_e32 v[94:95], 0
	v_mov_b64_e32 v[96:97], 0
	v_mov_b64_e32 v[98:99], 0
	v_mov_b64_e32 v[100:101], 0
	v_mov_b64_e32 v[102:103], 0
	v_mov_b64_e32 v[104:105], 0
	v_mov_b64_e32 v[106:107], 0
	v_mov_b64_e32 v[108:109], 0
	v_mov_b64_e32 v[110:111], 0
	v_mov_b64_e32 v[64:65], 0
	v_mov_b64_e32 v[66:67], 0
	v_mov_b64_e32 v[68:69], 0
	v_mov_b64_e32 v[70:71], 0
	v_mov_b64_e32 v[72:73], 0
	v_mov_b64_e32 v[74:75], 0
	v_mov_b64_e32 v[76:77], 0
	v_mov_b64_e32 v[78:79], 0
	v_mov_b64_e32 v[48:49], 0
	v_mov_b64_e32 v[50:51], 0
	v_mov_b64_e32 v[52:53], 0
	v_mov_b64_e32 v[54:55], 0
	v_mov_b64_e32 v[56:57], 0
	v_mov_b64_e32 v[58:59], 0
	v_mov_b64_e32 v[60:61], 0
	v_mov_b64_e32 v[62:63], 0
	v_mov_b64_e32 v[16:17], 0
	v_mov_b64_e32 v[18:19], 0
	v_mov_b64_e32 v[20:21], 0
	v_mov_b64_e32 v[22:23], 0
	v_mov_b64_e32 v[24:25], 0
	v_mov_b64_e32 v[26:27], 0
	v_mov_b64_e32 v[28:29], 0
	v_mov_b64_e32 v[30:31], 0
	v_mov_b64_e32 v[32:33], 0
	v_mov_b64_e32 v[34:35], 0
	v_mov_b64_e32 v[36:37], 0
	v_mov_b64_e32 v[38:39], 0
	v_mov_b64_e32 v[40:41], 0
	v_mov_b64_e32 v[42:43], 0
	v_mov_b64_e32 v[44:45], 0
	v_mov_b64_e32 v[46:47], 0
	v_mov_b64_e32 v[0:1], 0
	v_mov_b64_e32 v[2:3], 0
	v_mov_b64_e32 v[4:5], 0
	v_mov_b64_e32 v[6:7], 0
	v_mov_b64_e32 v[8:9], 0
	v_mov_b64_e32 v[10:11], 0
	v_mov_b64_e32 v[12:13], 0
	v_mov_b64_e32 v[14:15], 0
	s_waitcnt vmcnt(4)
	s_barrier
	ds_read_b128 v[144:147], v180 offset:0
	ds_read_b128 v[128:131], v176 offset:0
	ds_read_b128 v[148:151], v180 offset:4096
	ds_read_b128 v[132:135], v176 offset:4096
	ds_read_b128 v[136:139], v176 offset:8192
	ds_read_b128 v[140:143], v176 offset:12288
	s_movk_i32 s99, 7

; DI int tidx() { int t = threadIdx.x; asm volatile("" : "+v"(t)); return t; }
; DI void gemm_wide(const bf16_t* __restrict__ W, int ldw, const bf16_t* __restrict__ X, int ldx, int nkt,
;                   f32x16 (&acc)[4][2], bf16_t* lds) {
;   const int tid = tidx(), lane = tid & 63, wv = tid >> 6, wn = wv & 1, wm = wv >> 1;
;   const int lr = lane & 31, lh = lane >> 5;
;   const int lrow = tid >> 3, lkc = (tid & 7) * 8;
;   const bf16_t* wp = W + (size_t)lrow * ldw + lkc;
;   const bf16_t* xp = X + (size_t)lrow * ldx + lkc;
;   const size_t wst = (size_t)64 * ldw, xst = (size_t)64 * ldx;
;   u32x4 rw0, rw1, rw2, rw3, rx0, rx1, rx2, rx3;
;     ...
;   u32x4 sw0, sw1, sw2, sw3, sx0, sx1, sx2, sx3;
;     ...
;   __syncthreads();
;   GW_GLOAD(0)
;   GW_LSTORE(0)
;   GW_GLOAD(1)
;   GW_GLOAD_B(nkt > 2 ? 2 : nkt - 1)
;   __syncthreads();
; DI void phase_up(const P& p, int layer, bf16_t* sm, const Geo& ge) {
;     ...
;   TileWalk tw(16, ge);
;   int mt_, nt_, mt_have = -1;
;   float rs0 = 0.f, rs1 = 0.f;
;   while (tw.next(mt_, nt_)) {
;     if (mt_ != mt_have) {
;       rs0 = row_rstd(part, mt_ * 256 + wm * 64 + lr);
;       rs1 = row_rstd(part, mt_ * 256 + wm * 64 + 32 + lr);
;       mt_have = mt_;
;     }
;     f32x16 acc[4][2]; zero_acc8(acc);
;     gemm_wide(W + (size_t)nt_ * 256 * LDK1, LDK1, X + (size_t)mt_ * 256 * LDK1, LDK1, 16, acc, sm);
.LBB0_1145:
	s_lshl_b32 s0, s4, 3
	s_ashr_i32 s1, s5, 3
	s_add_i32 s0, s1, s0
	s_mul_i32 s8, s0, 0x88000
	s_mul_hi_i32 s1, s0, 0x88000
	s_add_u32 s8, s2, s8
	s_addc_u32 s9, s3, s1
	s_mul_i32 s1, s6, 0x88000
	s_add_u32 s26, s14, s1
	s_addc_u32 s27, s15, 0
	v_and_b32_e32 v128, 63, v195
	v_lshrrev_b32_e32 v129, 6, v195
	v_and_b32_e32 v130, 31, v128
	v_lshrrev_b32_e32 v131, 5, v128
	v_bfe_u32 v132, v130, 1, 3
	v_lshlrev_b32_e32 v133, 7, v130
	v_xor_b32_e32 v134, v131, v132
	v_lshl_add_u32 v135, v134, 4, v133
	v_and_b32_e32 v136, 1, v129
	v_lshlrev_b32_e32 v136, 14, v136
	v_lshrrev_b32_e32 v137, 1, v129
	v_lshlrev_b32_e32 v137, 13, v137
	v_add_u32_e32 v137, 0x10000, v137
	v_readfirstlane_b32 s98, v129
	v_add_u32_e32 v176, v136, v135
	v_xor_b32_e32 v177, 32, v176
	v_xor_b32_e32 v178, 64, v176
	v_xor_b32_e32 v179, 0x60, v176
	v_add_u32_e32 v180, v137, v135
	v_xor_b32_e32 v181, 32, v180
	v_xor_b32_e32 v182, 64, v180
	v_xor_b32_e32 v183, 0x60, v180
	s_lshl_b32 s98, s98, 12
	s_movk_i32 s100, 2176
	v_lshrrev_b32_e32 v138, 3, v128
	v_lshl_add_u32 v138, v129, 5, v138
	v_mul_lo_u32 v139, v138, s100
	v_and_b32_e32 v140, 7, v128
	v_lshrrev_b32_e32 v141, 4, v128
	v_xor_b32_e32 v142, v140, v141
	v_xor_b32_e32 v143, 4, v142
	v_lshl_add_u32 v184, v142, 4, v139
	v_lshl_add_u32 v185, v143, 4, v139
	v_add_u32_e32 v185, 0x4400, v185
	v_add_u32_e32 v186, 0x8800, v184
	v_add_u32_e32 v187, 0x8800, v185
	s_barrier
	s_mov_b32 m0, s98
	s_nop 0
	global_load_lds_dwordx4 v184, s[8:9]
	s_add_u32 m0, s98, 0x400
	s_nop 0
	global_load_lds_dwordx4 v185, s[8:9]
	s_add_u32 m0, s98, 0x800
	s_nop 0
	global_load_lds_dwordx4 v186, s[8:9]
	s_add_u32 m0, s98, 0xc00
	s_nop 0
	global_load_lds_dwordx4 v187, s[8:9]
	s_add_u32 s8, s8, 0x80
	s_addc_u32 s9, s9, 0
	s_add_u32 m0, s98, 0x10000
	s_nop 0
	global_load_lds_dwordx4 v184, s[26:27]
	s_add_u32 m0, s98, 0x10400
	s_nop 0
	global_load_lds_dwordx4 v185, s[26:27]
	s_add_u32 m0, s98, 0x10800
	s_nop 0
	global_load_lds_dwordx4 v186, s[26:27]
	s_add_u32 m0, s98, 0x10c00
	s_nop 0
	global_load_lds_dwordx4 v187, s[26:27]
	s_add_u32 s26, s26, 0x80
	s_addc_u32 s27, s27, 0
	s_add_u32 m0, s98, 0x8000
	s_nop 0
	global_load_lds_dwordx4 v184, s[8:9]
	s_add_u32 m0, s98, 0x8400
	s_nop 0
	global_load_lds_dwordx4 v185, s[8:9]
	s_add_u32 m0, s98, 0x8800
	s_nop 0
	global_load_lds_dwordx4 v186, s[8:9]
	s_add_u32 m0, s98, 0x8c00
	s_nop 0
	global_load_lds_dwordx4 v187, s[8:9]
	s_add_u32 s8, s8, 0x80
	s_addc_u32 s9, s9, 0
	v_mov_b64_e32 v[112:113], 0
	v_mov_b64_e32 v[114:115], 0
	v_mov_b64_e32 v[116:117], 0
	v_mov_b64_e32 v[118:119], 0
	v_mov_b64_e32 v[120:121], 0
	v_mov_b64_e32 v[122:123], 0
	v_mov_b64_e32 v[124:125], 0
	v_mov_b64_e32 v[126:127], 0
	v_mov_b64_e32 v[64:65], 0
	v_mov_b64_e32 v[66:67], 0
	v_mov_b64_e32 v[68:69], 0
	v_mov_b64_e32 v[70:71], 0
	v_mov_b64_e32 v[72:73], 0
	v_mov_b64_e32 v[74:75], 0
	v_mov_b64_e32 v[76:77], 0
	v_mov_b64_e32 v[78:79], 0
	v_mov_b64_e32 v[96:97], 0
	v_mov_b64_e32 v[98:99], 0
	v_mov_b64_e32 v[100:101], 0
	v_mov_b64_e32 v[102:103], 0
	v_mov_b64_e32 v[104:105], 0
	v_mov_b64_e32 v[106:107], 0
	v_mov_b64_e32 v[108:109], 0
	v_mov_b64_e32 v[110:111], 0
	v_mov_b64_e32 v[32:33], 0
	v_mov_b64_e32 v[34:35], 0
	v_mov_b64_e32 v[36:37], 0
	v_mov_b64_e32 v[38:39], 0
	v_mov_b64_e32 v[40:41], 0
	v_mov_b64_e32 v[42:43], 0
	v_mov_b64_e32 v[44:45], 0
	v_mov_b64_e32 v[46:47], 0
	v_mov_b64_e32 v[80:81], 0
	v_mov_b64_e32 v[82:83], 0
	v_mov_b64_e32 v[84:85], 0
	v_mov_b64_e32 v[86:87], 0
	v_mov_b64_e32 v[88:89], 0
	v_mov_b64_e32 v[90:91], 0
	v_mov_b64_e32 v[92:93], 0
	v_mov_b64_e32 v[94:95], 0
	v_mov_b64_e32 v[16:17], 0
	v_mov_b64_e32 v[18:19], 0
	v_mov_b64_e32 v[20:21], 0
	v_mov_b64_e32 v[22:23], 0
	v_mov_b64_e32 v[24:25], 0
	v_mov_b64_e32 v[26:27], 0
	v_mov_b64_e32 v[28:29], 0
	v_mov_b64_e32 v[30:31], 0
	v_mov_b64_e32 v[48:49], 0
	v_mov_b64_e32 v[50:51], 0
	v_mov_b64_e32 v[52:53], 0
	v_mov_b64_e32 v[54:55], 0
	v_mov_b64_e32 v[56:57], 0
	v_mov_b64_e32 v[58:59], 0
	v_mov_b64_e32 v[60:61], 0
	v_mov_b64_e32 v[62:63], 0
	v_mov_b64_e32 v[0:1], 0
	v_mov_b64_e32 v[2:3], 0
	v_mov_b64_e32 v[4:5], 0
	v_mov_b64_e32 v[6:7], 0
	v_mov_b64_e32 v[8:9], 0
	v_mov_b64_e32 v[10:11], 0
	v_mov_b64_e32 v[12:13], 0
	v_mov_b64_e32 v[14:15], 0
	s_waitcnt vmcnt(4)
	s_barrier
	ds_read_b128 v[144:147], v180 offset:0
	ds_read_b128 v[128:131], v176 offset:0
	ds_read_b128 v[148:151], v180 offset:4096
	ds_read_b128 v[132:135], v176 offset:4096
	ds_read_b128 v[136:139], v176 offset:8192
	ds_read_b128 v[140:143], v176 offset:12288
	s_movk_i32 s99, 7

; DI int tidx() { int t = threadIdx.x; asm volatile("" : "+v"(t)); return t; }
; DI void gemm_wide(const bf16_t* __restrict__ W, int ldw, const bf16_t* __restrict__ X, int ldx, int nkt,
;                   f32x16 (&acc)[4][2], bf16_t* lds) {
;   const int tid = tidx(), lane = tid & 63, wv = tid >> 6, wn = wv & 1, wm = wv >> 1;
;   const int lr = lane & 31, lh = lane >> 5;
;   const int lrow = tid >> 3, lkc = (tid & 7) * 8;
;   const bf16_t* wp = W + (size_t)lrow * ldw + lkc;
;   const bf16_t* xp = X + (size_t)lrow * ldx + lkc;
;   const size_t wst = (size_t)64 * ldw, xst = (size_t)64 * ldx;
;   u32x4 rw0, rw1, rw2, rw3, rx0, rx1, rx2, rx3;
;     ...
;   u32x4 sw0, sw1, sw2, sw3, sx0, sx1, sx2, sx3;
;     ...
;   __syncthreads();
;   GW_GLOAD(0)
;   GW_LSTORE(0)
;   GW_GLOAD(1)
;   GW_GLOAD_B(nkt > 2 ? 2 : nkt - 1)
;   __syncthreads();
; DI void phase_resid(const P& p, const bf16_t* W, const bf16_t* X, int K, bf16_t* sm, const Geo& ge, bool last) {
;   const int tid = tidx(), lane = tid & 63, wv = tid >> 6, wn = wv & 1, wm = wv >> 1;
;   const int lr = lane & 31, lh = lane >> 5;
;   bf16_t* xb = (bf16_t*)(p.ws + O_XB);
;   float* part = (float*)(p.ws + O_PART);
;   TileWalk tw(4, ge);
;   int mt_, nt_;
;   while (tw.next(mt_, nt_)) {
;     f32x16 acc[4][2]; zero_acc8(acc);
;     const int ldk = K + 64;
;     gemm_wide(W + (size_t)nt_ * 256 * ldk, ldk, X + (size_t)mt_ * 256 * ldk, ldk, K / 64, acc, sm);
.LBB0_1161:
	s_cmp_gt_i32 s27, 63
	s_cselect_b64 s[6:7], -1, 0
	s_cmp_lt_i32 s27, 64
	s_mov_b64 s[4:5], -1
	s_mov_b32 s8, s54
	s_cbranch_scc0 .LBB0_1181
	s_ashr_i32 s8, s27, 3
	s_cmp_lt_i32 s8, 4
	s_cbranch_scc0 .LBB0_1199
	s_and_b32 s5, s27, 7
	s_or_b32 s4, s5, s55
	s_mul_i32 s28, s8, 0x208000
	s_mul_hi_i32 s9, s8, 0x208000
	s_add_u32 s28, s25, s28
	s_addc_u32 s29, s26, s9
	s_mul_i32 s9, s4, 0x208000
	s_add_u32 s30, s58, s9
	s_addc_u32 s31, s59, 0
	v_and_b32_e32 v128, 63, v195
	v_lshrrev_b32_e32 v129, 6, v195
	v_and_b32_e32 v130, 31, v128
	v_lshrrev_b32_e32 v131, 5, v128
	v_bfe_u32 v132, v130, 1, 3
	v_lshlrev_b32_e32 v133, 7, v130
	v_xor_b32_e32 v134, v131, v132
	v_lshl_add_u32 v135, v134, 4, v133
	v_and_b32_e32 v136, 1, v129
	v_lshlrev_b32_e32 v136, 14, v136
	v_lshrrev_b32_e32 v137, 1, v129
	v_lshlrev_b32_e32 v137, 13, v137
	v_add_u32_e32 v137, 0x10000, v137
	v_readfirstlane_b32 s98, v129
	v_add_u32_e32 v176, v136, v135
	v_xor_b32_e32 v177, 32, v176
	v_xor_b32_e32 v178, 64, v176
	v_xor_b32_e32 v179, 0x60, v176
	v_add_u32_e32 v180, v137, v135
	v_xor_b32_e32 v181, 32, v180
	v_xor_b32_e32 v182, 64, v180
	v_xor_b32_e32 v183, 0x60, v180
	s_lshl_b32 s98, s98, 12
	s_movk_i32 s100, 8320
	v_lshrrev_b32_e32 v138, 3, v128
	v_lshl_add_u32 v138, v129, 5, v138
	v_mul_lo_u32 v139, v138, s100
	v_and_b32_e32 v140, 7, v128
	v_lshrrev_b32_e32 v141, 4, v128
	v_xor_b32_e32 v142, v140, v141
	v_xor_b32_e32 v143, 4, v142
	v_lshl_add_u32 v184, v142, 4, v139
	v_lshl_add_u32 v185, v143, 4, v139
	v_add_u32_e32 v185, 0x10400, v185
	v_add_u32_e32 v186, 0x20800, v184
	v_add_u32_e32 v187, 0x20800, v185
	s_barrier
	s_mov_b32 m0, s98
	s_nop 0
	global_load_lds_dwordx4 v184, s[28:29]
	s_add_u32 m0, s98, 0x400
	s_nop 0
	global_load_lds_dwordx4 v185, s[28:29]
	s_add_u32 m0, s98, 0x800
	s_nop 0
	global_load_lds_dwordx4 v186, s[28:29]
	s_add_u32 m0, s98, 0xc00
	s_nop 0
	global_load_lds_dwordx4 v187, s[28:29]
	s_add_u32 s28, s28, 0x80
	s_addc_u32 s29, s29, 0
	s_add_u32 m0, s98, 0x10000
	s_nop 0
	global_load_lds_dwordx4 v184, s[30:31]
	s_add_u32 m0, s98, 0x10400
	s_nop 0
	global_load_lds_dwordx4 v185, s[30:31]
	s_add_u32 m0, s98, 0x10800
	s_nop 0
	global_load_lds_dwordx4 v186, s[30:31]
	s_add_u32 m0, s98, 0x10c00
	s_nop 0
	global_load_lds_dwordx4 v187, s[30:31]
	s_add_u32 s30, s30, 0x80
	s_addc_u32 s31, s31, 0
	s_add_u32 m0, s98, 0x8000
	s_nop 0
	global_load_lds_dwordx4 v184, s[28:29]
	s_add_u32 m0, s98, 0x8400
	s_nop 0
	global_load_lds_dwordx4 v185, s[28:29]
	s_add_u32 m0, s98, 0x8800
	s_nop 0
	global_load_lds_dwordx4 v186, s[28:29]
	s_add_u32 m0, s98, 0x8c00
	s_nop 0
	global_load_lds_dwordx4 v187, s[28:29]
	s_add_u32 s28, s28, 0x80
	s_addc_u32 s29, s29, 0
	v_mov_b64_e32 v[112:113], 0
	v_mov_b64_e32 v[114:115], 0
	v_mov_b64_e32 v[116:117], 0
	v_mov_b64_e32 v[118:119], 0
	v_mov_b64_e32 v[120:121], 0
	v_mov_b64_e32 v[122:123], 0
	v_mov_b64_e32 v[124:125], 0
	v_mov_b64_e32 v[126:127], 0
	v_mov_b64_e32 v[80:81], 0
	v_mov_b64_e32 v[82:83], 0
	v_mov_b64_e32 v[84:85], 0
	v_mov_b64_e32 v[86:87], 0
	v_mov_b64_e32 v[88:89], 0
	v_mov_b64_e32 v[90:91], 0
	v_mov_b64_e32 v[92:93], 0
	v_mov_b64_e32 v[94:95], 0
	v_mov_b64_e32 v[96:97], 0
	v_mov_b64_e32 v[98:99], 0
	v_mov_b64_e32 v[100:101], 0
	v_mov_b64_e32 v[102:103], 0
	v_mov_b64_e32 v[104:105], 0
	v_mov_b64_e32 v[106:107], 0
	v_mov_b64_e32 v[108:109], 0
	v_mov_b64_e32 v[110:111], 0
	v_mov_b64_e32 v[64:65], 0
	v_mov_b64_e32 v[66:67], 0
	v_mov_b64_e32 v[68:69], 0
	v_mov_b64_e32 v[70:71], 0
	v_mov_b64_e32 v[72:73], 0
	v_mov_b64_e32 v[74:75], 0
	v_mov_b64_e32 v[76:77], 0
	v_mov_b64_e32 v[78:79], 0
	v_mov_b64_e32 v[48:49], 0
	v_mov_b64_e32 v[50:51], 0
	v_mov_b64_e32 v[52:53], 0
	v_mov_b64_e32 v[54:55], 0
	v_mov_b64_e32 v[56:57], 0
	v_mov_b64_e32 v[58:59], 0
	v_mov_b64_e32 v[60:61], 0
	v_mov_b64_e32 v[62:63], 0
	v_mov_b64_e32 v[16:17], 0
	v_mov_b64_e32 v[18:19], 0
	v_mov_b64_e32 v[20:21], 0
	v_mov_b64_e32 v[22:23], 0
	v_mov_b64_e32 v[24:25], 0
	v_mov_b64_e32 v[26:27], 0
	v_mov_b64_e32 v[28:29], 0
	v_mov_b64_e32 v[30:31], 0
	v_mov_b64_e32 v[32:33], 0
	v_mov_b64_e32 v[34:35], 0
	v_mov_b64_e32 v[36:37], 0
	v_mov_b64_e32 v[38:39], 0
	v_mov_b64_e32 v[40:41], 0
	v_mov_b64_e32 v[42:43], 0
	v_mov_b64_e32 v[44:45], 0
	v_mov_b64_e32 v[46:47], 0
	v_mov_b64_e32 v[0:1], 0
	v_mov_b64_e32 v[2:3], 0
	v_mov_b64_e32 v[4:5], 0
	v_mov_b64_e32 v[6:7], 0
	v_mov_b64_e32 v[8:9], 0
	v_mov_b64_e32 v[10:11], 0
	v_mov_b64_e32 v[12:13], 0
	v_mov_b64_e32 v[14:15], 0
	s_waitcnt vmcnt(4)
	s_barrier
	ds_read_b128 v[144:147], v180 offset:0
	ds_read_b128 v[128:131], v176 offset:0
	ds_read_b128 v[148:151], v180 offset:4096
	ds_read_b128 v[132:135], v176 offset:4096
	ds_read_b128 v[136:139], v176 offset:8192
	ds_read_b128 v[140:143], v176 offset:12288
	s_movk_i32 s99, 31
